# gemm_small<2,4> (sample rows of the gated projections): second pass's fragment loads issued together with the first pass's, counted vmcnt
# speedup vs baseline: 1.0029x; 1.0017x over previous
; DI int obid() { int b = blockIdx.x; asm volatile("" : "+s"(b)); return b; }
; template <int KIND, int KSTEPS  >
; DI void gemm_small(KP P, const bf16_t* A, int lda, const bf16_t* Bt, int ldb, int N, bf16_t* C, int ldc, char* lds) {
;     ...
;     for (int task = obid(); task < ntask; task += G) {
;         const int cb = (task & 7) + 8 * (task >> 6), rb = (task >> 3) & 7, row0 = MP + rb * 32, col0 = cb * 32;
; #pragma unroll
;         for (int pass = 0; pass < (KIND == 2 ? 2 : 1); ++pass) {
;             const bf16_t* ap = A + pass * 512 + (long)(row0 + r) * lda + w * (KSTEPS * 16) + 8 * hh;
;             const bf16_t* bp = (pass ? P->WpbT : Bt) + (long)(col0 + r) * ldb + w * (KSTEPS * 16) + 8 * hh;
;             f32x16 acc;
; #pragma unroll
;             for (int i = 0; i < 16; ++i) acc[i] = 0.f;
;             constexpr int UN = KSTEPS > 11 ? 11 : KSTEPS;
; #pragma unroll 1
;             for (int s0 = 0; s0 < KSTEPS; s0 += UN) {
;                 bf16x8 af[UN], bf[UN];
; #pragma unroll
;                 for (int s = 0; s < UN; ++s) { af[s] = *(const bf16x8*)(ap + (s0 + s) * 16); bf[s] = *(const bf16x8*)(bp + (s0 + s) * 16); }
; #pragma unroll
;                 for (int s = 0; s < UN; ++s) acc = MFMA32(bf[s], af[s], acc);
;             }
;             float* pp = part + ((pass * 8 + w) * 32 + r) * 32 + 4 * hh;
; #pragma unroll
;             for (int g = 0; g < 4; ++g) *(f32x4*)(pp + 8 * g) = (f32x4){acc[4 * g], acc[4 * g + 1], acc[4 * g + 2], acc[4 * g + 3]};
;         }
;         __syncthreads();
;         {
;             const int e = tid * 2, rr = e >> 5, cc = e & 31;
;             f32x2 s1 = {0.f, 0.f}, s2 = {0.f, 0.f};
; #pragma unroll
;             for (int ww = 0; ww < 8; ++ww) { s1 += *(const f32x2*)(part + (ww * 32 + rr) * 32 + cc); if (KIND == 2) s2 += *(const f32x2*)(part + ((8 + ww) * 32 + rr) * 32 + cc); }
;             const long row = row0 + rr; const int col = col0 + cc;
;             if (KIND == 1) { s1[0] = sigmoidf_(s1[0]); s1[1] = sigmoidf_(s1[1]); }
;             if (KIND == 2) { const unsigned ga = *(const unsigned*)(P->gates + row * 2048 + col), gb = *(const unsigned*)(P->gates + row * 2048 + 1024 + col);
;                 s1[0] = s1[0] * bf_lo(ga) + s2[0] * bf_lo(gb); s1[1] = s1[1] * bf_hi(ga) + s2[1] * bf_hi(gb); }
;             *(unsigned*)(C + row * ldc + col) = pk2(s1[0], s1[1]);
;         }
;         __syncthreads();
.LBB0_1081:
	s_lshr_b32 s15, s7, 3
	s_and_b32 s14, s7, 7
	s_and_b32 s15, s15, 0x7fffff8
	s_or_b32 s14, s15, s14
	s_lshl_b32 s14, s14, 5
	s_and_b32 s15, s12, 0xe0
	v_or_b32_e32 v0, s14, v22
	s_bitset1_b32 s15, 14
	v_ashrrev_i32_e32 v1, 31, v0
	v_lshlrev_b64 v[52:53], 10, v[0:1]
	v_or_b32_e32 v0, s15, v22
	v_lshlrev_b32_e32 v140, 11, v0
	v_lshl_add_u64 v[54:55], v[16:17], 0, v[140:141]
	v_lshl_add_u64 v[8:9], v[18:19], 0, v[52:53]
	global_load_dwordx4 v[0:3], v[54:55], off
	global_load_dwordx4 v[4:7], v[8:9], off
	global_load_dwordx4 v[28:31], v[54:55], off offset:32
	global_load_dwordx4 v[32:35], v[8:9], off offset:32
	global_load_dwordx4 v[36:39], v[54:55], off offset:64
	global_load_dwordx4 v[40:43], v[8:9], off offset:64
	global_load_dwordx4 v[44:47], v[54:55], off offset:96
	global_load_dwordx4 v[48:51], v[8:9], off offset:96
	v_lshl_add_u64 v[62:63], v[20:21], 0, v[52:53]
	global_load_dwordx4 v[64:67], v[54:55], off offset:1024
	global_load_dwordx4 v[68:71], v[62:63], off
	global_load_dwordx4 v[72:75], v[54:55], off offset:1056
	global_load_dwordx4 v[76:79], v[62:63], off offset:32
	global_load_dwordx4 v[80:83], v[54:55], off offset:1088
	global_load_dwordx4 v[84:87], v[62:63], off offset:64
	global_load_dwordx4 v[88:91], v[54:55], off offset:1120
	global_load_dwordx4 v[92:95], v[62:63], off offset:96
	s_add_i32 s7, s7, s6
	s_add_i32 s12, s12, s13
	s_cmpk_gt_i32 s7, 0xff
	s_waitcnt vmcnt(8)
	v_mfma_f32_32x32x16_bf16 v[0:15], v[4:7], v[0:3], 0
	v_mfma_f32_32x32x16_bf16 v[0:15], v[32:35], v[28:31], v[0:15]
	v_mfma_f32_32x32x16_bf16 v[0:15], v[40:43], v[36:39], v[0:15]
	v_mfma_f32_32x32x16_bf16 v[0:15], v[48:51], v[44:47], v[0:15]
	s_nop 11
	ds_write_b128 v26, v[0:3]
	ds_write_b128 v26, v[4:7] offset:32
	ds_write_b128 v26, v[8:11] offset:64
	ds_write_b128 v26, v[12:15] offset:96
	s_nop 3
	s_waitcnt vmcnt(6)
	v_mfma_f32_32x32x16_bf16 v[0:15], v[68:71], v[64:67], 0
	s_waitcnt vmcnt(4)
	v_mfma_f32_32x32x16_bf16 v[0:15], v[76:79], v[72:75], v[0:15]
	s_waitcnt vmcnt(2)
	v_mfma_f32_32x32x16_bf16 v[0:15], v[84:87], v[80:83], v[0:15]
	s_waitcnt vmcnt(0)
	v_mfma_f32_32x32x16_bf16 v[0:15], v[92:95], v[88:91], v[0:15]
	s_nop 11
	ds_write_b128 v26, v[0:3] offset:32768
	ds_write_b128 v26, v[4:7] offset:32800
	ds_write_b128 v26, v[8:11] offset:32832
	ds_write_b128 v26, v[12:15] offset:32864
	s_waitcnt lgkmcnt(0)
	s_barrier
	ds_read2st64_b64 v[0:3], v25 offset1:8
	ds_read2st64_b64 v[4:7], v25 offset0:64 offset1:72
	s_waitcnt lgkmcnt(1)
	v_pk_add_f32 v[0:1], v[0:1], 0 op_sel_hi:[1,0]
	s_waitcnt lgkmcnt(0)
	v_pk_add_f32 v[4:5], v[4:5], 0 op_sel_hi:[1,0]
	v_pk_add_f32 v[8:9], v[0:1], v[2:3]
	v_pk_add_f32 v[10:11], v[4:5], v[6:7]
	ds_read2st64_b64 v[0:3], v25 offset0:16 offset1:24
	ds_read2st64_b64 v[4:7], v25 offset0:80 offset1:88
	s_waitcnt lgkmcnt(1)
	v_pk_add_f32 v[0:1], v[8:9], v[0:1]
	s_waitcnt lgkmcnt(0)
	v_pk_add_f32 v[4:5], v[10:11], v[4:5]
	v_pk_add_f32 v[8:9], v[0:1], v[2:3]
	v_pk_add_f32 v[10:11], v[4:5], v[6:7]
	ds_read2st64_b64 v[0:3], v25 offset0:32 offset1:40
	ds_read2st64_b64 v[4:7], v25 offset0:96 offset1:104
	s_waitcnt lgkmcnt(1)
	v_pk_add_f32 v[0:1], v[8:9], v[0:1]
	s_waitcnt lgkmcnt(0)
	v_pk_add_f32 v[4:5], v[10:11], v[4:5]
	v_pk_add_f32 v[8:9], v[0:1], v[2:3]
	v_pk_add_f32 v[10:11], v[4:5], v[6:7]
	ds_read2st64_b64 v[0:3], v25 offset0:48 offset1:56
	ds_read2st64_b64 v[4:7], v25 offset0:112 offset1:120
	s_waitcnt lgkmcnt(1)
	v_pk_add_f32 v[0:1], v[8:9], v[0:1]
	s_waitcnt lgkmcnt(0)
	v_pk_add_f32 v[4:5], v[10:11], v[4:5]
	v_pk_add_f32 v[0:1], v[0:1], v[2:3]
	v_pk_add_f32 v[2:3], v[4:5], v[6:7]
	v_add_u32_e32 v4, s15, v23
	v_ashrrev_i32_e32 v5, 31, v4
	v_or_b32_e32 v6, s14, v24
	v_lshlrev_b64 v[8:9], 12, v[4:5]
	v_ashrrev_i32_e32 v7, 31, v6
	v_lshl_add_u64 v[8:9], s[8:9], 0, v[8:9]
	v_lshlrev_b64 v[6:7], 1, v[6:7]
	v_lshl_add_u64 v[8:9], v[8:9], 0, v[6:7]
	global_load_dword v11, v[8:9], off
	global_load_dword v12, v[8:9], off offset:2048
	s_waitcnt vmcnt(1)
	v_lshlrev_b32_e32 v8, 16, v11
	s_waitcnt vmcnt(0)
	v_lshlrev_b32_e32 v10, 16, v12
	v_and_b32_e32 v9, 0xffff0000, v11
	v_and_b32_e32 v11, 0xffff0000, v12
	v_pk_mul_f32 v[2:3], v[2:3], v[10:11]
	s_nop 0
	v_pk_fma_f32 v[0:1], v[0:1], v[8:9], v[2:3]
	s_nop 0
	v_cvt_pk_bf16_f32 v2, v0, v1
	v_lshlrev_b64 v[0:1], 11, v[4:5]
	v_lshl_add_u64 v[0:1], s[10:11], 0, v[0:1]
	v_lshl_add_u64 v[0:1], v[0:1], 0, v[6:7]
	global_store_dword v[0:1], v2, off
	s_barrier
	s_cbranch_scc0 .LBB0_1081
